# conv loop: first-iteration vmcnt waits hoisted out of the loop (no store drain per batch)
# baseline (speedup 1.0000x reference)
.LBB0_498:
	s_or_b64 exec, exec, s[14:15]
	v_lshl_add_u64 v[84:85], v[84:85], 1, s[4:5]
	s_mov_b64 s[14:15], 0xe00000
	v_cndmask_b32_e64 v2, 4, 2, s[38:39]
	v_lshl_add_u64 v[134:135], v[84:85], 0, s[14:15]
	v_add_u32_e32 v176, 7, v1
	s_mov_b32 s15, 0
	s_mov_b64 s[38:39], 0
	s_waitcnt vmcnt(0)
.LBB0_499:
	v_lshlrev_b32_e32 v174, 16, v116
	v_and_b32_e32 v175, 0xffff0000, v116
	v_lshlrev_b32_e32 v172, 16, v124
	v_and_b32_e32 v173, 0xffff0000, v124
	v_pk_fma_f32 v[142:143], v[8:9], v[174:175], v[40:41]
	v_lshlrev_b32_e32 v170, 16, v120
	v_and_b32_e32 v171, 0xffff0000, v120
	v_pk_fma_f32 v[142:143], v[16:17], v[172:173], v[142:143]
	v_lshlrev_b32_e32 v152, 16, v128
	v_and_b32_e32 v153, 0xffff0000, v128
	v_pk_fma_f32 v[142:143], v[24:25], v[170:171], v[142:143]
	v_lshlrev_b32_e32 v168, 16, v117
	v_pk_fma_f32 v[142:143], v[32:33], v[152:153], v[142:143]
	v_and_b32_e32 v169, 0xffff0000, v117
	v_mul_f32_e32 v116, 0xbfb8aa3b, v142
	v_exp_f32_e32 v116, v116
	v_lshlrev_b32_e32 v166, 16, v125
	v_and_b32_e32 v167, 0xffff0000, v125
	v_lshlrev_b32_e32 v164, 16, v121
	v_add_f32_e32 v116, 1.0, v116
	v_rcp_f32_e32 v144, v116
	v_mul_f32_e32 v116, 0xbfb8aa3b, v143
	v_exp_f32_e32 v116, v116
	v_and_b32_e32 v165, 0xffff0000, v121
	v_lshlrev_b32_e32 v162, 16, v129
	v_and_b32_e32 v163, 0xffff0000, v129
	v_add_f32_e32 v116, 1.0, v116
	v_rcp_f32_e32 v145, v116
	v_pk_fma_f32 v[116:117], v[10:11], v[168:169], v[42:43]
	v_lshlrev_b32_e32 v160, 16, v118
	v_pk_fma_f32 v[116:117], v[18:19], v[166:167], v[116:117]
	v_and_b32_e32 v161, 0xffff0000, v118
	v_pk_fma_f32 v[116:117], v[26:27], v[164:165], v[116:117]
	v_lshlrev_b32_e32 v158, 16, v126
	v_pk_fma_f32 v[116:117], v[34:35], v[162:163], v[116:117]
	v_and_b32_e32 v159, 0xffff0000, v126
	v_mul_f32_e32 v120, 0xbfb8aa3b, v116
	v_mul_f32_e32 v121, 0xbfb8aa3b, v117
	v_exp_f32_e32 v120, v120
	v_exp_f32_e32 v121, v121
	v_lshlrev_b32_e32 v156, 16, v122
	v_and_b32_e32 v157, 0xffff0000, v122
	v_add_f32_e32 v120, 1.0, v120
	v_add_f32_e32 v121, 1.0, v121
	v_rcp_f32_e32 v120, v120
	v_rcp_f32_e32 v121, v121
	v_lshlrev_b32_e32 v154, 16, v130
	v_and_b32_e32 v155, 0xffff0000, v130
	v_lshlrev_b32_e32 v150, 16, v119
	v_pk_mul_f32 v[120:121], v[116:117], v[120:121]
	v_pk_fma_f32 v[116:117], v[4:5], v[160:161], v[36:37]
	v_and_b32_e32 v151, 0xffff0000, v119
	v_pk_fma_f32 v[116:117], v[12:13], v[158:159], v[116:117]
	v_pk_mul_f32 v[148:149], v[142:143], v[144:145]
	v_pk_fma_f32 v[116:117], v[20:21], v[156:157], v[116:117]
	v_lshlrev_b32_e32 v144, 16, v127
	v_pk_fma_f32 v[116:117], v[28:29], v[154:155], v[116:117]
	v_and_b32_e32 v145, 0xffff0000, v127
	v_mul_f32_e32 v118, 0xbfb8aa3b, v116
	v_exp_f32_e32 v118, v118
	v_lshlrev_b32_e32 v142, 16, v123
	v_and_b32_e32 v143, 0xffff0000, v123
	v_lshlrev_b32_e32 v128, 16, v131
	v_add_f32_e32 v118, 1.0, v118
	v_rcp_f32_e32 v124, v118
	v_mul_f32_e32 v118, 0xbfb8aa3b, v117
	v_exp_f32_e32 v118, v118
	v_and_b32_e32 v129, 0xffff0000, v131
	s_add_i32 s14, s15, 1
	v_cmp_lt_u32_e32 vcc, s14, v2
	v_add_f32_e32 v118, 1.0, v118
	v_rcp_f32_e32 v125, v118
	v_mov_b32_e32 v84, s15
	v_mov_b32_e32 v85, s14
	v_cndmask_b32_e32 v84, v84, v85, vcc
	v_pk_mul_f32 v[124:125], v[116:117], v[124:125]
	v_pk_fma_f32 v[116:117], v[6:7], v[150:151], v[38:39]
	v_lshl_add_u32 v112, v84, 3, v1
	v_pk_fma_f32 v[116:117], v[14:15], v[144:145], v[116:117]
	v_mad_i64_i32 v[84:85], s[16:17], v112, s95, v[132:133]
	v_pk_fma_f32 v[116:117], v[22:23], v[142:143], v[116:117]
	v_or_b32_e32 v88, 1, v112
	v_pk_fma_f32 v[116:117], v[30:31], v[128:129], v[116:117]
	v_or_b32_e32 v92, 2, v112
	v_mul_f32_e32 v118, 0xbfb8aa3b, v116
	v_mul_f32_e32 v119, 0xbfb8aa3b, v117
	v_exp_f32_e32 v118, v118
	v_exp_f32_e32 v119, v119
	v_or_b32_e32 v96, 3, v112
	v_or_b32_e32 v100, 4, v112
	v_add_f32_e32 v118, 1.0, v118
	v_add_f32_e32 v119, 1.0, v119
	v_rcp_f32_e32 v118, v118
	v_rcp_f32_e32 v119, v119
	v_or_b32_e32 v104, 5, v112
	v_or_b32_e32 v108, 6, v112
	v_or_b32_e32 v112, 7, v112
	v_pk_mul_f32 v[122:123], v[116:117], v[118:119]
	v_cvt_pk_bf16_f32 v117, v120, v121
	v_add_u32_e32 v120, -3, v176
	v_pk_fma_f32 v[44:45], v[8:9], v[44:45], v[40:41]
	v_mad_i64_i32 v[88:89], s[16:17], v88, s95, v[132:133]
	v_mad_i64_i32 v[92:93], s[16:17], v92, s95, v[132:133]
	v_mad_i64_i32 v[96:97], s[16:17], v96, s95, v[132:133]
	v_mad_i64_i32 v[100:101], s[16:17], v100, s95, v[132:133]
	v_mad_i64_i32 v[104:105], s[16:17], v104, s95, v[132:133]
	v_mad_i64_i32 v[108:109], s[16:17], v108, s95, v[132:133]
	v_mad_i64_i32 v[112:113], s[16:17], v112, s95, v[132:133]
	v_cvt_pk_bf16_f32 v116, v148, v149
	v_cvt_pk_bf16_f32 v118, v124, v125
	v_cvt_pk_bf16_f32 v119, v122, v123
	v_mad_i64_i32 v[120:121], s[16:17], v120, s95, v[134:135]
	v_pk_fma_f32 v[44:45], v[16:17], v[48:49], v[44:45]
	global_load_dwordx4 v[84:87], v[84:85], off nt
	v_pk_fma_f32 v[44:45], v[24:25], v[52:53], v[44:45]
	global_load_dwordx4 v[88:91], v[88:89], off nt
	v_pk_fma_f32 v[46:47], v[10:11], v[46:47], v[42:43]
	global_load_dwordx4 v[92:95], v[92:93], off nt
	v_pk_fma_f32 v[46:47], v[18:19], v[50:51], v[46:47]
	global_load_dwordx4 v[96:99], v[96:97], off nt
	v_pk_fma_f32 v[46:47], v[26:27], v[54:55], v[46:47]
	global_load_dwordx4 v[100:103], v[100:101], off nt
	v_pk_fma_f32 v[56:57], v[4:5], v[56:57], v[36:37]
	global_load_dwordx4 v[104:107], v[104:105], off nt
	v_pk_fma_f32 v[56:57], v[12:13], v[60:61], v[56:57]
	global_load_dwordx4 v[108:111], v[108:109], off nt
	v_pk_fma_f32 v[56:57], v[20:21], v[64:65], v[56:57]
	global_load_dwordx4 v[112:115], v[112:113], off nt
	v_pk_fma_f32 v[58:59], v[6:7], v[58:59], v[38:39]
	global_store_dwordx4 v[120:121], v[116:119], off
	v_pk_fma_f32 v[58:59], v[14:15], v[62:63], v[58:59]
	v_add_u32_e32 v136, -7, v176
	v_lshlrev_b32_e32 v118, 16, v80
	v_and_b32_e32 v119, 0xffff0000, v80
	v_pk_fma_f32 v[44:45], v[32:33], v[118:119], v[44:45]
	v_add_u32_e32 v116, -2, v176
	v_mul_f32_e32 v80, 0xbfb8aa3b, v44
	v_exp_f32_e32 v80, v80
	v_mad_i64_i32 v[148:149], s[16:17], v116, s95, v[134:135]
	v_add_u32_e32 v116, -1, v176
	v_add_f32_e32 v80, 1.0, v80
	v_mad_i64_i32 v[130:131], s[16:17], v116, s95, v[134:135]
	v_rcp_f32_e32 v116, v80
	v_mul_f32_e32 v80, 0xbfb8aa3b, v45
	v_exp_f32_e32 v80, v80
	v_pk_fma_f32 v[58:59], v[22:23], v[66:67], v[58:59]
	v_mad_i64_i32 v[146:147], s[16:17], v136, s95, v[134:135]
	v_add_f32_e32 v80, 1.0, v80
	v_rcp_f32_e32 v117, v80
	v_add_u32_e32 v136, -6, v176
	v_mad_i64_i32 v[140:141], s[16:17], v136, s95, v[134:135]
	v_pk_mul_f32 v[44:45], v[44:45], v[116:117]
	v_add_u32_e32 v136, -5, v176
	v_cvt_pk_bf16_f32 v124, v44, v45
	v_pk_fma_f32 v[44:45], v[8:9], v[48:49], v[40:41]
	v_mad_i64_i32 v[138:139], s[16:17], v136, s95, v[134:135]
	v_pk_fma_f32 v[44:45], v[16:17], v[52:53], v[44:45]
	v_add_u32_e32 v136, -4, v176
	v_pk_fma_f32 v[44:45], v[24:25], v[118:119], v[44:45]
	v_mad_i64_i32 v[136:137], s[16:17], v136, s95, v[134:135]
	v_pk_fma_f32 v[44:45], v[32:33], v[174:175], v[44:45]
	v_cmp_eq_u32_e32 vcc, s14, v2
	v_mul_f32_e32 v48, 0xbfb8aa3b, v44
	v_mul_f32_e32 v49, 0xbfb8aa3b, v45
	v_exp_f32_e32 v48, v48
	v_exp_f32_e32 v49, v49
	s_or_b64 s[38:39], vcc, s[38:39]
	s_mov_b32 s15, s14
	v_add_f32_e32 v48, 1.0, v48
	v_add_f32_e32 v49, 1.0, v49
	v_rcp_f32_e32 v48, v48
	v_rcp_f32_e32 v49, v49
	s_nop 0
	v_pk_mul_f32 v[44:45], v[44:45], v[48:49]
	s_nop 0
	v_cvt_pk_bf16_f32 v120, v44, v45
	v_pk_fma_f32 v[44:45], v[8:9], v[52:53], v[40:41]
	s_nop 0
	v_pk_fma_f32 v[44:45], v[16:17], v[118:119], v[44:45]
	s_nop 0
	v_pk_fma_f32 v[44:45], v[24:25], v[174:175], v[44:45]
	s_nop 0
	v_pk_fma_f32 v[44:45], v[32:33], v[172:173], v[44:45]
	s_nop 0
	v_mul_f32_e32 v48, 0xbfb8aa3b, v44
	v_mul_f32_e32 v49, 0xbfb8aa3b, v45
	v_exp_f32_e32 v48, v48
	v_exp_f32_e32 v49, v49
	v_add_f32_e32 v48, 1.0, v48
	v_add_f32_e32 v49, 1.0, v49
	v_rcp_f32_e32 v48, v48
	v_rcp_f32_e32 v49, v49
	s_nop 0
	v_pk_mul_f32 v[44:45], v[44:45], v[48:49]
	s_nop 0
	v_cvt_pk_bf16_f32 v116, v44, v45
	v_pk_fma_f32 v[44:45], v[8:9], v[118:119], v[40:41]
	s_nop 0
	v_pk_fma_f32 v[44:45], v[16:17], v[174:175], v[44:45]
	s_nop 0
	v_pk_fma_f32 v[44:45], v[24:25], v[172:173], v[44:45]
	s_nop 0
	v_pk_fma_f32 v[44:45], v[32:33], v[170:171], v[44:45]
	s_nop 0
	v_mul_f32_e32 v48, 0xbfb8aa3b, v44
	v_mul_f32_e32 v49, 0xbfb8aa3b, v45
	v_exp_f32_e32 v48, v48
	v_exp_f32_e32 v49, v49
	v_add_f32_e32 v48, 1.0, v48
	v_add_f32_e32 v49, 1.0, v49
	v_rcp_f32_e32 v48, v48
	v_rcp_f32_e32 v49, v49
	s_nop 0
	v_pk_mul_f32 v[44:45], v[44:45], v[48:49]
	v_pk_fma_f32 v[48:49], v[8:9], v[172:173], v[40:41]
	v_cvt_pk_bf16_f32 v80, v44, v45
	v_pk_fma_f32 v[48:49], v[16:17], v[170:171], v[48:49]
	v_lshlrev_b32_e32 v44, 16, v76
	v_and_b32_e32 v45, 0xffff0000, v76
	v_pk_fma_f32 v[48:49], v[24:25], v[152:153], v[48:49]
	s_nop 0
	v_pk_fma_f32 v[48:49], v[32:33], v[44:45], v[48:49]
	s_nop 0
	v_mul_f32_e32 v52, 0xbfb8aa3b, v48
	v_mul_f32_e32 v53, 0xbfb8aa3b, v49
	v_exp_f32_e32 v52, v52
	v_exp_f32_e32 v53, v53
	v_add_f32_e32 v52, 1.0, v52
	v_add_f32_e32 v53, 1.0, v53
	v_rcp_f32_e32 v52, v52
	v_rcp_f32_e32 v53, v53
	s_nop 0
	v_pk_mul_f32 v[48:49], v[48:49], v[52:53]
	v_pk_fma_f32 v[52:53], v[8:9], v[170:171], v[40:41]
	v_cvt_pk_bf16_f32 v76, v48, v49
	v_pk_fma_f32 v[52:53], v[16:17], v[152:153], v[52:53]
	v_lshlrev_b32_e32 v48, 16, v72
	v_and_b32_e32 v49, 0xffff0000, v72
	v_pk_fma_f32 v[52:53], v[24:25], v[44:45], v[52:53]
	s_nop 0
	v_pk_fma_f32 v[52:53], v[32:33], v[48:49], v[52:53]
	s_nop 0
	v_mul_f32_e32 v72, 0xbfb8aa3b, v52
	v_exp_f32_e32 v72, v72
	s_nop 0
	v_add_f32_e32 v72, 1.0, v72
	v_rcp_f32_e32 v118, v72
	v_mul_f32_e32 v72, 0xbfb8aa3b, v53
	v_exp_f32_e32 v72, v72
	s_nop 0
	v_add_f32_e32 v72, 1.0, v72
	v_rcp_f32_e32 v119, v72
	s_nop 0
	v_pk_mul_f32 v[52:53], v[52:53], v[118:119]
	v_pk_fma_f32 v[118:119], v[8:9], v[152:153], v[40:41]
	v_cvt_pk_bf16_f32 v72, v52, v53
	v_pk_fma_f32 v[118:119], v[16:17], v[44:45], v[118:119]
	v_lshlrev_b32_e32 v52, 16, v68
	v_and_b32_e32 v53, 0xffff0000, v68
	v_pk_fma_f32 v[118:119], v[24:25], v[48:49], v[118:119]
	s_nop 0
	v_pk_fma_f32 v[118:119], v[32:33], v[52:53], v[118:119]
	s_nop 0
	v_mul_f32_e32 v68, 0xbfb8aa3b, v118
	v_exp_f32_e32 v68, v68
	s_nop 0
	v_add_f32_e32 v68, 1.0, v68
	v_rcp_f32_e32 v122, v68
	v_mul_f32_e32 v68, 0xbfb8aa3b, v119
	v_exp_f32_e32 v68, v68
	s_nop 0
	v_add_f32_e32 v68, 1.0, v68
	v_rcp_f32_e32 v123, v68
	s_nop 0
	v_pk_mul_f32 v[152:153], v[118:119], v[122:123]
	v_lshlrev_b32_e32 v118, 16, v81
	v_and_b32_e32 v119, 0xffff0000, v81
	v_pk_fma_f32 v[46:47], v[34:35], v[118:119], v[46:47]
	s_nop 0
	v_mul_f32_e32 v68, 0xbfb8aa3b, v46
	v_exp_f32_e32 v68, v68
	s_nop 0
	v_add_f32_e32 v68, 1.0, v68
	v_rcp_f32_e32 v122, v68
	v_mul_f32_e32 v68, 0xbfb8aa3b, v47
	v_exp_f32_e32 v68, v68
	s_nop 0
	v_add_f32_e32 v68, 1.0, v68
	v_rcp_f32_e32 v123, v68
	s_nop 0
	v_pk_mul_f32 v[46:47], v[46:47], v[122:123]
	s_nop 0
	v_cvt_pk_bf16_f32 v125, v46, v47
	v_pk_fma_f32 v[46:47], v[10:11], v[50:51], v[42:43]
	s_nop 0
	v_pk_fma_f32 v[46:47], v[18:19], v[54:55], v[46:47]
	s_nop 0
	v_pk_fma_f32 v[46:47], v[26:27], v[118:119], v[46:47]
	s_nop 0
	v_pk_fma_f32 v[46:47], v[34:35], v[168:169], v[46:47]
	s_nop 0
	v_mul_f32_e32 v50, 0xbfb8aa3b, v46
	v_mul_f32_e32 v51, 0xbfb8aa3b, v47
	v_exp_f32_e32 v50, v50
	v_exp_f32_e32 v51, v51
	v_add_f32_e32 v50, 1.0, v50
	v_add_f32_e32 v51, 1.0, v51
	v_rcp_f32_e32 v50, v50
	v_rcp_f32_e32 v51, v51
	s_nop 0
	v_pk_mul_f32 v[46:47], v[46:47], v[50:51]
	s_nop 0
	v_cvt_pk_bf16_f32 v121, v46, v47
	v_pk_fma_f32 v[46:47], v[10:11], v[54:55], v[42:43]
	s_nop 0
	v_pk_fma_f32 v[46:47], v[18:19], v[118:119], v[46:47]
	s_nop 0
	v_pk_fma_f32 v[46:47], v[26:27], v[168:169], v[46:47]
	s_nop 0
	v_pk_fma_f32 v[46:47], v[34:35], v[166:167], v[46:47]
	s_nop 0
	v_mul_f32_e32 v50, 0xbfb8aa3b, v46
	v_mul_f32_e32 v51, 0xbfb8aa3b, v47
	v_exp_f32_e32 v50, v50
	v_exp_f32_e32 v51, v51
	v_add_f32_e32 v50, 1.0, v50
	v_add_f32_e32 v51, 1.0, v51
	v_rcp_f32_e32 v50, v50
	v_rcp_f32_e32 v51, v51
	s_nop 0
	v_pk_mul_f32 v[46:47], v[46:47], v[50:51]
	s_nop 0
	v_cvt_pk_bf16_f32 v117, v46, v47
	v_pk_fma_f32 v[46:47], v[10:11], v[118:119], v[42:43]
	s_nop 0
	v_pk_fma_f32 v[46:47], v[18:19], v[168:169], v[46:47]
	s_nop 0
	v_pk_fma_f32 v[46:47], v[26:27], v[166:167], v[46:47]
	s_nop 0
	v_pk_fma_f32 v[46:47], v[34:35], v[164:165], v[46:47]
	s_nop 0
	v_mul_f32_e32 v50, 0xbfb8aa3b, v46
	v_mul_f32_e32 v51, 0xbfb8aa3b, v47
	v_exp_f32_e32 v50, v50
	v_exp_f32_e32 v51, v51
	v_add_f32_e32 v50, 1.0, v50
	v_add_f32_e32 v51, 1.0, v51
	v_rcp_f32_e32 v50, v50
	v_rcp_f32_e32 v51, v51
	s_nop 0
	v_pk_mul_f32 v[46:47], v[46:47], v[50:51]
	v_pk_fma_f32 v[50:51], v[10:11], v[166:167], v[42:43]
	v_cvt_pk_bf16_f32 v81, v46, v47
	v_pk_fma_f32 v[50:51], v[18:19], v[164:165], v[50:51]
	v_lshlrev_b32_e32 v46, 16, v77
	v_and_b32_e32 v47, 0xffff0000, v77
	v_pk_fma_f32 v[50:51], v[26:27], v[162:163], v[50:51]
	s_nop 0
	v_pk_fma_f32 v[50:51], v[34:35], v[46:47], v[50:51]
	s_nop 0
	v_mul_f32_e32 v54, 0xbfb8aa3b, v50
	v_mul_f32_e32 v55, 0xbfb8aa3b, v51
	v_exp_f32_e32 v54, v54
	v_exp_f32_e32 v55, v55
	v_add_f32_e32 v54, 1.0, v54
	v_add_f32_e32 v55, 1.0, v55
	v_rcp_f32_e32 v54, v54
	v_rcp_f32_e32 v55, v55
	s_nop 0
	v_pk_mul_f32 v[50:51], v[50:51], v[54:55]
	v_pk_fma_f32 v[54:55], v[10:11], v[164:165], v[42:43]
	v_cvt_pk_bf16_f32 v77, v50, v51
	v_pk_fma_f32 v[54:55], v[18:19], v[162:163], v[54:55]
	v_lshlrev_b32_e32 v50, 16, v73
	v_and_b32_e32 v51, 0xffff0000, v73
	v_pk_fma_f32 v[54:55], v[26:27], v[46:47], v[54:55]
	s_nop 0
	v_pk_fma_f32 v[54:55], v[34:35], v[50:51], v[54:55]
	s_nop 0
	v_mul_f32_e32 v68, 0xbfb8aa3b, v54
	v_exp_f32_e32 v68, v68
	s_nop 0
	v_add_f32_e32 v68, 1.0, v68
	v_rcp_f32_e32 v118, v68
	v_mul_f32_e32 v68, 0xbfb8aa3b, v55
	v_exp_f32_e32 v68, v68
	s_nop 0
	v_add_f32_e32 v68, 1.0, v68
	v_rcp_f32_e32 v119, v68
	s_nop 0
	v_pk_mul_f32 v[54:55], v[54:55], v[118:119]
	s_nop 0
	v_cvt_pk_bf16_f32 v73, v54, v55
	v_lshlrev_b32_e32 v54, 16, v69
	v_and_b32_e32 v55, 0xffff0000, v69
	v_pk_fma_f32 v[68:69], v[10:11], v[162:163], v[42:43]
	v_lshlrev_b32_e32 v162, 16, v82
	v_pk_fma_f32 v[68:69], v[18:19], v[46:47], v[68:69]
	v_and_b32_e32 v163, 0xffff0000, v82
	v_pk_fma_f32 v[68:69], v[26:27], v[50:51], v[68:69]
	v_pk_fma_f32 v[56:57], v[28:29], v[162:163], v[56:57]
	v_pk_fma_f32 v[68:69], v[34:35], v[54:55], v[68:69]
	v_mul_f32_e32 v82, 0xbfb8aa3b, v56
	v_mul_f32_e32 v118, 0xbfb8aa3b, v68
	v_mul_f32_e32 v119, 0xbfb8aa3b, v69
	v_exp_f32_e32 v118, v118
	v_exp_f32_e32 v119, v119
	v_exp_f32_e32 v82, v82
	v_add_f32_e32 v118, 1.0, v118
	v_add_f32_e32 v119, 1.0, v119
	v_rcp_f32_e32 v118, v118
	v_rcp_f32_e32 v119, v119
	v_add_f32_e32 v82, 1.0, v82
	v_pk_mul_f32 v[68:69], v[68:69], v[118:119]
	v_rcp_f32_e32 v118, v82
	v_mul_f32_e32 v82, 0xbfb8aa3b, v57
	v_exp_f32_e32 v82, v82
	s_nop 0
	v_add_f32_e32 v82, 1.0, v82
	v_rcp_f32_e32 v119, v82
	s_nop 0
	v_pk_mul_f32 v[56:57], v[56:57], v[118:119]
	s_nop 0
	v_cvt_pk_bf16_f32 v126, v56, v57
	v_pk_fma_f32 v[56:57], v[4:5], v[60:61], v[36:37]
	s_nop 0
	v_pk_fma_f32 v[56:57], v[12:13], v[64:65], v[56:57]
	s_nop 0
	v_pk_fma_f32 v[56:57], v[20:21], v[162:163], v[56:57]
	s_nop 0
	v_pk_fma_f32 v[56:57], v[28:29], v[160:161], v[56:57]
	s_nop 0
	v_mul_f32_e32 v60, 0xbfb8aa3b, v56
	v_mul_f32_e32 v61, 0xbfb8aa3b, v57
	v_exp_f32_e32 v60, v60
	v_exp_f32_e32 v61, v61
	v_add_f32_e32 v60, 1.0, v60
	v_add_f32_e32 v61, 1.0, v61
	v_rcp_f32_e32 v60, v60
	v_rcp_f32_e32 v61, v61
	s_nop 0
	v_pk_mul_f32 v[56:57], v[56:57], v[60:61]
	s_nop 0
	v_cvt_pk_bf16_f32 v122, v56, v57
	v_pk_fma_f32 v[56:57], v[4:5], v[64:65], v[36:37]
	s_nop 0
	v_pk_fma_f32 v[56:57], v[12:13], v[162:163], v[56:57]
	s_nop 0
	v_pk_fma_f32 v[56:57], v[20:21], v[160:161], v[56:57]
	s_nop 0
	v_pk_fma_f32 v[56:57], v[28:29], v[158:159], v[56:57]
	s_nop 0
	v_mul_f32_e32 v60, 0xbfb8aa3b, v56
	v_mul_f32_e32 v61, 0xbfb8aa3b, v57
	v_exp_f32_e32 v60, v60
	v_exp_f32_e32 v61, v61
	v_add_f32_e32 v60, 1.0, v60
	v_add_f32_e32 v61, 1.0, v61
	v_rcp_f32_e32 v60, v60
	v_rcp_f32_e32 v61, v61
	s_nop 0
	v_pk_mul_f32 v[56:57], v[56:57], v[60:61]
	s_nop 0
	v_cvt_pk_bf16_f32 v118, v56, v57
	v_pk_fma_f32 v[56:57], v[4:5], v[162:163], v[36:37]
	s_nop 0
	v_pk_fma_f32 v[56:57], v[12:13], v[160:161], v[56:57]
	s_nop 0
	v_pk_fma_f32 v[56:57], v[20:21], v[158:159], v[56:57]
	s_nop 0
	v_pk_fma_f32 v[56:57], v[28:29], v[156:157], v[56:57]
	s_nop 0
	v_mul_f32_e32 v60, 0xbfb8aa3b, v56
	v_mul_f32_e32 v61, 0xbfb8aa3b, v57
	v_exp_f32_e32 v60, v60
	v_exp_f32_e32 v61, v61
	v_add_f32_e32 v60, 1.0, v60
	v_add_f32_e32 v61, 1.0, v61
	v_rcp_f32_e32 v60, v60
	v_rcp_f32_e32 v61, v61
	s_nop 0
	v_pk_mul_f32 v[56:57], v[56:57], v[60:61]
	v_pk_fma_f32 v[60:61], v[4:5], v[158:159], v[36:37]
	v_cvt_pk_bf16_f32 v82, v56, v57
	v_pk_fma_f32 v[60:61], v[12:13], v[156:157], v[60:61]
	v_lshlrev_b32_e32 v56, 16, v78
	v_and_b32_e32 v57, 0xffff0000, v78
	v_pk_fma_f32 v[60:61], v[20:21], v[154:155], v[60:61]
	s_nop 0
	v_pk_fma_f32 v[60:61], v[28:29], v[56:57], v[60:61]
	s_nop 0
	v_mul_f32_e32 v64, 0xbfb8aa3b, v60
	v_mul_f32_e32 v65, 0xbfb8aa3b, v61
	v_exp_f32_e32 v64, v64
	v_exp_f32_e32 v65, v65
	v_add_f32_e32 v64, 1.0, v64
	v_add_f32_e32 v65, 1.0, v65
	v_rcp_f32_e32 v64, v64
	v_rcp_f32_e32 v65, v65
	s_nop 0
	v_pk_mul_f32 v[60:61], v[60:61], v[64:65]
	v_pk_fma_f32 v[64:65], v[4:5], v[156:157], v[36:37]
	v_cvt_pk_bf16_f32 v78, v60, v61
	v_pk_fma_f32 v[64:65], v[12:13], v[154:155], v[64:65]
	v_lshlrev_b32_e32 v60, 16, v74
	v_and_b32_e32 v61, 0xffff0000, v74
	v_pk_fma_f32 v[64:65], v[20:21], v[56:57], v[64:65]
	v_pk_fma_f32 v[154:155], v[4:5], v[154:155], v[36:37]
	v_pk_fma_f32 v[64:65], v[28:29], v[60:61], v[64:65]
	v_pk_fma_f32 v[154:155], v[12:13], v[56:57], v[154:155]
	v_mul_f32_e32 v74, 0xbfb8aa3b, v64
	v_exp_f32_e32 v74, v74
	v_pk_fma_f32 v[154:155], v[20:21], v[60:61], v[154:155]
	v_add_f32_e32 v74, 1.0, v74
	v_rcp_f32_e32 v156, v74
	v_mul_f32_e32 v74, 0xbfb8aa3b, v65
	v_exp_f32_e32 v74, v74
	s_nop 0
	v_add_f32_e32 v74, 1.0, v74
	v_rcp_f32_e32 v157, v74
	s_nop 0
	v_pk_mul_f32 v[64:65], v[64:65], v[156:157]
	s_nop 0
	v_cvt_pk_bf16_f32 v74, v64, v65
	v_lshlrev_b32_e32 v64, 16, v70
	v_and_b32_e32 v65, 0xffff0000, v70
	v_pk_fma_f32 v[154:155], v[28:29], v[64:65], v[154:155]
	s_nop 0
	v_mul_f32_e32 v70, 0xbfb8aa3b, v154
	v_exp_f32_e32 v70, v70
	s_nop 0
	v_add_f32_e32 v70, 1.0, v70
	v_rcp_f32_e32 v156, v70
	v_mul_f32_e32 v70, 0xbfb8aa3b, v155
	v_exp_f32_e32 v70, v70
	s_nop 0
	v_add_f32_e32 v70, 1.0, v70
	v_rcp_f32_e32 v157, v70
	s_nop 0
	v_pk_mul_f32 v[154:155], v[154:155], v[156:157]
	v_lshlrev_b32_e32 v156, 16, v83
	v_and_b32_e32 v157, 0xffff0000, v83
	v_pk_fma_f32 v[58:59], v[30:31], v[156:157], v[58:59]
	s_nop 0
	v_mul_f32_e32 v70, 0xbfb8aa3b, v58
	v_exp_f32_e32 v70, v70
	s_nop 0
	v_add_f32_e32 v70, 1.0, v70
	v_rcp_f32_e32 v158, v70
	v_mul_f32_e32 v70, 0xbfb8aa3b, v59
	v_exp_f32_e32 v70, v70
	s_nop 0
	v_add_f32_e32 v70, 1.0, v70
	v_rcp_f32_e32 v159, v70
	s_nop 0
	v_pk_mul_f32 v[58:59], v[58:59], v[158:159]
	s_nop 0
	v_cvt_pk_bf16_f32 v127, v58, v59
	v_pk_fma_f32 v[58:59], v[6:7], v[62:63], v[38:39]
	global_store_dwordx4 v[146:147], v[124:127], off
	v_pk_fma_f32 v[58:59], v[14:15], v[66:67], v[58:59]
	s_nop 0
	v_pk_fma_f32 v[58:59], v[22:23], v[156:157], v[58:59]
	s_waitcnt vmcnt(7)
	v_mov_b64_e32 v[126:127], v[94:95]
	v_pk_fma_f32 v[58:59], v[30:31], v[150:151], v[58:59]
	v_mov_b64_e32 v[124:125], v[92:93]
	v_mul_f32_e32 v62, 0xbfb8aa3b, v58
	v_mul_f32_e32 v63, 0xbfb8aa3b, v59
	v_exp_f32_e32 v62, v62
	v_exp_f32_e32 v63, v63
	v_add_f32_e32 v62, 1.0, v62
	v_add_f32_e32 v63, 1.0, v63
	v_rcp_f32_e32 v62, v62
	v_rcp_f32_e32 v63, v63
	s_nop 0
	v_pk_mul_f32 v[58:59], v[58:59], v[62:63]
	s_nop 0
	v_cvt_pk_bf16_f32 v123, v58, v59
	v_pk_fma_f32 v[58:59], v[6:7], v[66:67], v[38:39]
	global_store_dwordx4 v[140:141], v[120:123], off
	v_pk_fma_f32 v[58:59], v[14:15], v[156:157], v[58:59]
	s_nop 0
	v_pk_fma_f32 v[58:59], v[22:23], v[150:151], v[58:59]
	s_waitcnt vmcnt(7)
	v_mov_b64_e32 v[122:123], v[98:99]
	v_pk_fma_f32 v[58:59], v[30:31], v[144:145], v[58:59]
	v_mov_b64_e32 v[120:121], v[96:97]
	v_mul_f32_e32 v62, 0xbfb8aa3b, v58
	v_mul_f32_e32 v63, 0xbfb8aa3b, v59
	v_exp_f32_e32 v62, v62
	v_exp_f32_e32 v63, v63
	v_add_f32_e32 v62, 1.0, v62
	v_add_f32_e32 v63, 1.0, v63
	v_rcp_f32_e32 v62, v62
	v_rcp_f32_e32 v63, v63
	s_nop 0
	v_pk_mul_f32 v[58:59], v[58:59], v[62:63]
	s_nop 0
	v_cvt_pk_bf16_f32 v119, v58, v59
	v_pk_fma_f32 v[58:59], v[6:7], v[156:157], v[38:39]
	global_store_dwordx4 v[138:139], v[116:119], off
	v_pk_fma_f32 v[58:59], v[14:15], v[150:151], v[58:59]
	s_nop 0
	v_pk_fma_f32 v[58:59], v[22:23], v[144:145], v[58:59]
	v_mov_b64_e32 v[118:119], v[90:91]
	v_pk_fma_f32 v[58:59], v[30:31], v[142:143], v[58:59]
	v_mov_b64_e32 v[116:117], v[88:89]
	v_mul_f32_e32 v62, 0xbfb8aa3b, v58
	v_mul_f32_e32 v63, 0xbfb8aa3b, v59
	v_exp_f32_e32 v62, v62
	v_exp_f32_e32 v63, v63
	v_add_f32_e32 v62, 1.0, v62
	v_add_f32_e32 v63, 1.0, v63
	v_rcp_f32_e32 v62, v62
	v_rcp_f32_e32 v63, v63
	s_nop 0
	v_pk_mul_f32 v[58:59], v[58:59], v[62:63]
	v_pk_fma_f32 v[62:63], v[6:7], v[144:145], v[38:39]
	v_cvt_pk_bf16_f32 v83, v58, v59
	v_pk_fma_f32 v[62:63], v[14:15], v[142:143], v[62:63]
	v_lshlrev_b32_e32 v58, 16, v79
	v_and_b32_e32 v59, 0xffff0000, v79
	v_pk_fma_f32 v[62:63], v[22:23], v[128:129], v[62:63]
	global_store_dwordx4 v[136:137], v[80:83], off
	v_pk_fma_f32 v[62:63], v[30:31], v[58:59], v[62:63]
	s_nop 0
	v_mul_f32_e32 v66, 0xbfb8aa3b, v62
	v_mul_f32_e32 v67, 0xbfb8aa3b, v63
	v_exp_f32_e32 v66, v66
	v_exp_f32_e32 v67, v67
	v_mov_b64_e32 v[80:81], v[84:85]
	v_mov_b64_e32 v[82:83], v[86:87]
	v_add_f32_e32 v66, 1.0, v66
	v_add_f32_e32 v67, 1.0, v67
	v_rcp_f32_e32 v66, v66
	v_rcp_f32_e32 v67, v67
	s_nop 0
	v_pk_mul_f32 v[62:63], v[62:63], v[66:67]
	v_pk_fma_f32 v[66:67], v[6:7], v[142:143], v[38:39]
	v_cvt_pk_bf16_f32 v79, v62, v63
	v_pk_fma_f32 v[66:67], v[14:15], v[128:129], v[66:67]
	v_lshlrev_b32_e32 v62, 16, v75
	v_and_b32_e32 v63, 0xffff0000, v75
	v_pk_fma_f32 v[66:67], v[22:23], v[58:59], v[66:67]
	global_store_dwordx4 v[148:149], v[76:79], off
	v_pk_fma_f32 v[66:67], v[30:31], v[62:63], v[66:67]
	s_nop 0
	v_mul_f32_e32 v70, 0xbfb8aa3b, v66
	v_exp_f32_e32 v70, v70
	s_nop 0
	v_add_f32_e32 v70, 1.0, v70
	v_rcp_f32_e32 v76, v70
	v_mul_f32_e32 v70, 0xbfb8aa3b, v67
	v_exp_f32_e32 v70, v70
	s_nop 0
	v_add_f32_e32 v70, 1.0, v70
	v_rcp_f32_e32 v77, v70
	s_nop 0
	v_pk_mul_f32 v[66:67], v[66:67], v[76:77]
	s_nop 0
	v_cvt_pk_bf16_f32 v75, v66, v67
	v_lshlrev_b32_e32 v66, 16, v71
	v_and_b32_e32 v67, 0xffff0000, v71
	v_pk_fma_f32 v[70:71], v[6:7], v[128:129], v[38:39]
	global_store_dwordx4 v[130:131], v[72:75], off
	v_pk_fma_f32 v[70:71], v[14:15], v[58:59], v[70:71]
	s_waitcnt vmcnt(10)
	v_mov_b64_e32 v[130:131], v[102:103]
	v_pk_fma_f32 v[70:71], v[22:23], v[62:63], v[70:71]
	s_waitcnt vmcnt(9)
	v_mov_b64_e32 v[76:77], v[104:105]
	v_pk_fma_f32 v[70:71], v[30:31], v[66:67], v[70:71]
	v_mov_b64_e32 v[128:129], v[100:101]
	v_mul_f32_e32 v72, 0xbfb8aa3b, v70
	v_mul_f32_e32 v73, 0xbfb8aa3b, v71
	v_exp_f32_e32 v72, v72
	v_exp_f32_e32 v73, v73
	v_mov_b64_e32 v[78:79], v[106:107]
	v_add_f32_e32 v72, 1.0, v72
	v_add_f32_e32 v73, 1.0, v73
	v_rcp_f32_e32 v72, v72
	v_rcp_f32_e32 v73, v73
	s_nop 0
	v_pk_mul_f32 v[74:75], v[70:71], v[72:73]
	v_cvt_pk_bf16_f32 v70, v152, v153
	v_cvt_pk_bf16_f32 v71, v68, v69
	v_cvt_pk_bf16_f32 v72, v154, v155
	v_cvt_pk_bf16_f32 v73, v74, v75
	v_mad_i64_i32 v[68:69], s[16:17], v176, s95, v[134:135]
	global_store_dwordx4 v[68:69], v[70:73], off
	s_waitcnt vmcnt(8)
	v_mov_b64_e32 v[68:69], v[112:113]
	v_add_u32_e32 v176, 8, v176
	v_mov_b64_e32 v[72:73], v[108:109]
	v_mov_b64_e32 v[74:75], v[110:111]
	v_mov_b64_e32 v[70:71], v[114:115]
	s_andn2_b64 exec, exec, s[38:39]
	s_cbranch_execnz .LBB0_499
